# xcd barriers: per-XCD generation bump (and its wait) removed from the leader path, nothing polls that word any more
# baseline (speedup 1.0000x reference)
; __device__ __forceinline__ unsigned xb_add(unsigned* p, unsigned v) { return __hip_atomic_fetch_add(p, v, __ATOMIC_RELAXED, __HIP_MEMORY_SCOPE_AGENT); }
; __device__ __forceinline__ void xcd_barrier(const XcdBarrier& b) {
;     ...
;             __builtin_amdgcn_fence(__ATOMIC_ACQUIRE, "agent");
;             xb_add(&bar[XB_XGEN(b.x)], 1u);
;             asm volatile("s_waitcnt vmcnt(0)" ::: "memory");
.LBB0_127:
	s_or_b64 exec, exec, s[8:9]
	v_mov_b32_e32 v0, 0x2000
	v_mov_b32_e32 v1, 1
	s_waitcnt vmcnt(0)
	buffer_inv sc1
	s_waitcnt vmcnt(0)
